# p4 LRU apply: carry-in prelude issues all tile-summary loads at once (one wait); main loop prefetches next 8-row batch into spare regs
# speedup vs baseline: 1.0635x; 1.0011x over previous
; DEVI void apply_item(const Params& P, int l, int pass, int id, int tid) {
;     ...
;   const TokInfo t0 = tokinfo(base + lt0);
;   float hcur = 0.f;
;   if (!t0.sample) {
;     int jf = tile - (t0.t >> 7);
; #pragma unroll 4
;     for (int i = jf; i < tile; ++i) hcur = LS[(long)i * 2048 + ch] * hcur + LS[(long)i * 2048 + 1024 + ch];
;   }
.LBB0_532:
	s_andn2_b64 vcc, exec, s[82:83]
	v_mov_b32_e32 v12, 0
	s_cbranch_vccnz .LBB0_649
	s_and_b32 s52, s49, 0x300
	v_add_u32_e32 v2, s52, v91
	s_lshr_b32 s52, s50, 7
	s_sub_i32 s82, s51, s52
	v_lshlrev_b32_e32 v2, 2, v2
	s_ashr_i32 s83, s82, 31
	s_lshl_b64 s[54:55], s[82:83], 13
	s_add_u32 s54, s84, s54
	s_addc_u32 s55, s85, s55
	v_readlane_b32 s4, v252, 27
	s_add_u32 s54, s4, s54
	v_readlane_b32 s4, v252, 28
	s_addc_u32 s55, s4, s55
	v_mov_b32_e32 v14, 1.0
	v_mov_b32_e32 v220, 0
	v_mov_b32_e32 v15, 1.0
	v_mov_b32_e32 v221, 0
	v_mov_b32_e32 v16, 1.0
	v_mov_b32_e32 v222, 0
	v_mov_b32_e32 v17, 1.0
	v_mov_b32_e32 v223, 0
	v_mov_b32_e32 v18, 1.0
	v_mov_b32_e32 v224, 0
	v_mov_b32_e32 v19, 1.0
	v_mov_b32_e32 v225, 0
	v_mov_b32_e32 v20, 1.0
	v_mov_b32_e32 v226, 0
	v_mov_b32_e32 v21, 1.0
	v_mov_b32_e32 v227, 0
	v_mov_b32_e32 v28, 1.0
	v_mov_b32_e32 v228, 0
	v_mov_b32_e32 v29, 1.0
	v_mov_b32_e32 v229, 0
	v_mov_b32_e32 v30, 1.0
	v_mov_b32_e32 v230, 0
	v_mov_b32_e32 v31, 1.0
	v_mov_b32_e32 v231, 0
	v_mov_b32_e32 v32, 1.0
	v_mov_b32_e32 v232, 0
	v_mov_b32_e32 v33, 1.0
	v_mov_b32_e32 v233, 0
	v_mov_b32_e32 v34, 1.0
	v_mov_b32_e32 v234, 0
	v_mov_b32_e32 v35, 1.0
	v_mov_b32_e32 v235, 0
	v_mov_b32_e32 v36, 1.0
	v_mov_b32_e32 v236, 0
	v_mov_b32_e32 v37, 1.0
	v_mov_b32_e32 v237, 0
	v_mov_b32_e32 v38, 1.0
	v_mov_b32_e32 v238, 0
	v_mov_b32_e32 v39, 1.0
	v_mov_b32_e32 v239, 0
	v_mov_b32_e32 v40, 1.0
	v_mov_b32_e32 v240, 0
	v_mov_b32_e32 v41, 1.0
	v_mov_b32_e32 v241, 0
	v_mov_b32_e32 v42, 1.0
	v_mov_b32_e32 v242, 0
	v_mov_b32_e32 v43, 1.0
	v_mov_b32_e32 v243, 0
	v_mov_b32_e32 v44, 1.0
	v_mov_b32_e32 v244, 0
	v_mov_b32_e32 v45, 1.0
	v_mov_b32_e32 v245, 0
	v_mov_b32_e32 v46, 1.0
	v_mov_b32_e32 v246, 0
	v_mov_b32_e32 v47, 1.0
	v_mov_b32_e32 v247, 0
	v_mov_b32_e32 v48, 1.0
	v_mov_b32_e32 v248, 0
	v_mov_b32_e32 v50, 1.0
	v_mov_b32_e32 v249, 0
	global_load_dword v13, v2, s[54:55] offset:-4096
	global_load_dword v219, v2, s[54:55]
	s_cmp_lt_u32 s52, 2
	s_cbranch_scc1 .Lap_pre_w
	s_add_u32 s54, s54, 0x2000
	s_addc_u32 s55, s55, 0
	global_load_dword v14, v2, s[54:55] offset:-4096
	global_load_dword v220, v2, s[54:55]
	s_cmp_lt_u32 s52, 3
	s_cbranch_scc1 .Lap_pre_w
	s_add_u32 s54, s54, 0x2000
	s_addc_u32 s55, s55, 0
	global_load_dword v15, v2, s[54:55] offset:-4096
	global_load_dword v221, v2, s[54:55]
	s_cmp_lt_u32 s52, 4
	s_cbranch_scc1 .Lap_pre_w
	s_add_u32 s54, s54, 0x2000
	s_addc_u32 s55, s55, 0
	global_load_dword v16, v2, s[54:55] offset:-4096
	global_load_dword v222, v2, s[54:55]
	s_cmp_lt_u32 s52, 5
	s_cbranch_scc1 .Lap_pre_w
	s_add_u32 s54, s54, 0x2000
	s_addc_u32 s55, s55, 0
	global_load_dword v17, v2, s[54:55] offset:-4096
	global_load_dword v223, v2, s[54:55]
	s_cmp_lt_u32 s52, 6
	s_cbranch_scc1 .Lap_pre_w
	s_add_u32 s54, s54, 0x2000
	s_addc_u32 s55, s55, 0
	global_load_dword v18, v2, s[54:55] offset:-4096
	global_load_dword v224, v2, s[54:55]
	s_cmp_lt_u32 s52, 7
	s_cbranch_scc1 .Lap_pre_w
	s_add_u32 s54, s54, 0x2000
	s_addc_u32 s55, s55, 0
	global_load_dword v19, v2, s[54:55] offset:-4096
	global_load_dword v225, v2, s[54:55]
	s_cmp_lt_u32 s52, 8
	s_cbranch_scc1 .Lap_pre_w
	s_add_u32 s54, s54, 0x2000
	s_addc_u32 s55, s55, 0
	global_load_dword v20, v2, s[54:55] offset:-4096
	global_load_dword v226, v2, s[54:55]
	s_cmp_lt_u32 s52, 9
	s_cbranch_scc1 .Lap_pre_w
	s_add_u32 s54, s54, 0x2000
	s_addc_u32 s55, s55, 0
	global_load_dword v21, v2, s[54:55] offset:-4096
	global_load_dword v227, v2, s[54:55]
	s_cmp_lt_u32 s52, 10
	s_cbranch_scc1 .Lap_pre_w
	s_add_u32 s54, s54, 0x2000
	s_addc_u32 s55, s55, 0
	global_load_dword v28, v2, s[54:55] offset:-4096
	global_load_dword v228, v2, s[54:55]
	s_cmp_lt_u32 s52, 11
	s_cbranch_scc1 .Lap_pre_w
	s_add_u32 s54, s54, 0x2000
	s_addc_u32 s55, s55, 0
	global_load_dword v29, v2, s[54:55] offset:-4096
	global_load_dword v229, v2, s[54:55]
	s_cmp_lt_u32 s52, 12
	s_cbranch_scc1 .Lap_pre_w
	s_add_u32 s54, s54, 0x2000
	s_addc_u32 s55, s55, 0
	global_load_dword v30, v2, s[54:55] offset:-4096
	global_load_dword v230, v2, s[54:55]
	s_cmp_lt_u32 s52, 13
	s_cbranch_scc1 .Lap_pre_w
	s_add_u32 s54, s54, 0x2000
	s_addc_u32 s55, s55, 0
	global_load_dword v31, v2, s[54:55] offset:-4096
	global_load_dword v231, v2, s[54:55]
	s_cmp_lt_u32 s52, 14
	s_cbranch_scc1 .Lap_pre_w
	s_add_u32 s54, s54, 0x2000
	s_addc_u32 s55, s55, 0
	global_load_dword v32, v2, s[54:55] offset:-4096
	global_load_dword v232, v2, s[54:55]
	s_cmp_lt_u32 s52, 15
	s_cbranch_scc1 .Lap_pre_w
; DEVI void apply_item(const Params& P, int l, int pass, int id, int tid) {
;     ...
;   if (!t0.sample) {
;     int jf = tile - (t0.t >> 7);
; #pragma unroll 4
;     for (int i = jf; i < tile; ++i) hcur = LS[(long)i * 2048 + ch] * hcur + LS[(long)i * 2048 + 1024 + ch];
;   }
	s_add_u32 s54, s54, 0x2000
	s_addc_u32 s55, s55, 0
	global_load_dword v33, v2, s[54:55] offset:-4096
	global_load_dword v233, v2, s[54:55]
	s_cmp_lt_u32 s52, 16
	s_cbranch_scc1 .Lap_pre_w
	s_add_u32 s54, s54, 0x2000
	s_addc_u32 s55, s55, 0
	global_load_dword v34, v2, s[54:55] offset:-4096
	global_load_dword v234, v2, s[54:55]
	s_cmp_lt_u32 s52, 17
	s_cbranch_scc1 .Lap_pre_w
	s_add_u32 s54, s54, 0x2000
	s_addc_u32 s55, s55, 0
	global_load_dword v35, v2, s[54:55] offset:-4096
	global_load_dword v235, v2, s[54:55]
	s_cmp_lt_u32 s52, 18
	s_cbranch_scc1 .Lap_pre_w
	s_add_u32 s54, s54, 0x2000
	s_addc_u32 s55, s55, 0
	global_load_dword v36, v2, s[54:55] offset:-4096
	global_load_dword v236, v2, s[54:55]
	s_cmp_lt_u32 s52, 19
	s_cbranch_scc1 .Lap_pre_w
	s_add_u32 s54, s54, 0x2000
	s_addc_u32 s55, s55, 0
	global_load_dword v37, v2, s[54:55] offset:-4096
	global_load_dword v237, v2, s[54:55]
	s_cmp_lt_u32 s52, 20
	s_cbranch_scc1 .Lap_pre_w
	s_add_u32 s54, s54, 0x2000
	s_addc_u32 s55, s55, 0
	global_load_dword v38, v2, s[54:55] offset:-4096
	global_load_dword v238, v2, s[54:55]
	s_cmp_lt_u32 s52, 21
	s_cbranch_scc1 .Lap_pre_w
	s_add_u32 s54, s54, 0x2000
	s_addc_u32 s55, s55, 0
	global_load_dword v39, v2, s[54:55] offset:-4096
	global_load_dword v239, v2, s[54:55]
	s_cmp_lt_u32 s52, 22
	s_cbranch_scc1 .Lap_pre_w
	s_add_u32 s54, s54, 0x2000
	s_addc_u32 s55, s55, 0
	global_load_dword v40, v2, s[54:55] offset:-4096
	global_load_dword v240, v2, s[54:55]
	s_cmp_lt_u32 s52, 23
	s_cbranch_scc1 .Lap_pre_w
	s_add_u32 s54, s54, 0x2000
	s_addc_u32 s55, s55, 0
	global_load_dword v41, v2, s[54:55] offset:-4096
	global_load_dword v241, v2, s[54:55]
	s_cmp_lt_u32 s52, 24
	s_cbranch_scc1 .Lap_pre_w
	s_add_u32 s54, s54, 0x2000
	s_addc_u32 s55, s55, 0
	global_load_dword v42, v2, s[54:55] offset:-4096
	global_load_dword v242, v2, s[54:55]
	s_cmp_lt_u32 s52, 25
	s_cbranch_scc1 .Lap_pre_w
	s_add_u32 s54, s54, 0x2000
	s_addc_u32 s55, s55, 0
	global_load_dword v43, v2, s[54:55] offset:-4096
	global_load_dword v243, v2, s[54:55]
	s_cmp_lt_u32 s52, 26
	s_cbranch_scc1 .Lap_pre_w
	s_add_u32 s54, s54, 0x2000
	s_addc_u32 s55, s55, 0
	global_load_dword v44, v2, s[54:55] offset:-4096
	global_load_dword v244, v2, s[54:55]
	s_cmp_lt_u32 s52, 27
	s_cbranch_scc1 .Lap_pre_w
	s_add_u32 s54, s54, 0x2000
	s_addc_u32 s55, s55, 0
	global_load_dword v45, v2, s[54:55] offset:-4096
	global_load_dword v245, v2, s[54:55]
	s_cmp_lt_u32 s52, 28
	s_cbranch_scc1 .Lap_pre_w
	s_add_u32 s54, s54, 0x2000
	s_addc_u32 s55, s55, 0
	global_load_dword v46, v2, s[54:55] offset:-4096
	global_load_dword v246, v2, s[54:55]
	s_cmp_lt_u32 s52, 29
	s_cbranch_scc1 .Lap_pre_w
	s_add_u32 s54, s54, 0x2000
	s_addc_u32 s55, s55, 0
	global_load_dword v47, v2, s[54:55] offset:-4096
	global_load_dword v247, v2, s[54:55]
	s_cmp_lt_u32 s52, 30
	s_cbranch_scc1 .Lap_pre_w
	s_add_u32 s54, s54, 0x2000
	s_addc_u32 s55, s55, 0
	global_load_dword v48, v2, s[54:55] offset:-4096
	global_load_dword v248, v2, s[54:55]
	s_cmp_lt_u32 s52, 31
	s_cbranch_scc1 .Lap_pre_w
	s_add_u32 s54, s54, 0x2000
	s_addc_u32 s55, s55, 0
	global_load_dword v50, v2, s[54:55] offset:-4096
	global_load_dword v249, v2, s[54:55]
.Lap_pre_w:
	v_mov_b32_e32 v12, 0
	s_waitcnt vmcnt(0)
	v_fmac_f32_e32 v219, v12, v13
	v_fmac_f32_e32 v220, v219, v14
	v_fmac_f32_e32 v221, v220, v15
	v_fmac_f32_e32 v222, v221, v16
	v_fmac_f32_e32 v223, v222, v17
	v_fmac_f32_e32 v224, v223, v18
	v_fmac_f32_e32 v225, v224, v19
	v_fmac_f32_e32 v226, v225, v20
	v_fmac_f32_e32 v227, v226, v21
	v_fmac_f32_e32 v228, v227, v28
	v_fmac_f32_e32 v229, v228, v29
	v_fmac_f32_e32 v230, v229, v30
	v_fmac_f32_e32 v231, v230, v31
	v_fmac_f32_e32 v232, v231, v32
	v_fmac_f32_e32 v233, v232, v33
	v_fmac_f32_e32 v234, v233, v34
	v_fmac_f32_e32 v235, v234, v35
	v_fmac_f32_e32 v236, v235, v36
	v_fmac_f32_e32 v237, v236, v37
	v_fmac_f32_e32 v238, v237, v38
	v_fmac_f32_e32 v239, v238, v39
	v_fmac_f32_e32 v240, v239, v40
	v_fmac_f32_e32 v241, v240, v41
	v_fmac_f32_e32 v242, v241, v42
	v_fmac_f32_e32 v243, v242, v43
	v_fmac_f32_e32 v244, v243, v44
	v_fmac_f32_e32 v245, v244, v45
	v_fmac_f32_e32 v246, v245, v46
	v_fmac_f32_e32 v247, v246, v47
	v_fmac_f32_e32 v248, v247, v48
	v_fmac_f32_e32 v249, v248, v50
	v_mov_b32_e32 v12, v249
	s_branch .LBB0_649

; DEVI float b2f(bfu b) { return __uint_as_float(((unsigned)b) << 16); }
; DEVI void apply_item(const Params& P, int l, int pass, int id, int tid) {
;     ...
;   for (int r0 = 0; r0 < 128; r0 += 8) {
;     float av[8], uv[8], gv[8];
; #pragma unroll
;     for (int i = 0; i < 8; ++i) {
;       long row = lt0 + r0 + i;
;       av[i] = AU0[row * 1024 + ch]; uv[i] = AU1[row * 1024 + ch];
;       gv[i] = b2f(Z[row * NCOL + 4 * 1024 + ch]);
.LBB0_649:
	s_ashr_i32 s79, s78, 31
	s_add_i32 s51, s24, s47
	s_lshl_b64 s[52:53], s[78:79], 11
	s_add_u32 s52, s80, s52
	s_addc_u32 s53, s81, s53
	v_lshlrev_b64 v[6:7], 1, v[0:1]
	v_lshl_add_u64 v[4:5], s[52:53], 0, v[6:7]
	s_mul_i32 s52, s78, 0x6000
	s_mul_hi_i32 s53, s78, 0x6000
	s_add_u32 s52, s76, s52
	s_addc_u32 s53, s77, s53
	v_lshl_add_u64 v[6:7], s[52:53], 0, v[6:7]
	s_lshl_b64 s[52:53], s[78:79], 12
	v_readlane_b32 s4, v254, 44
	s_add_u32 s52, s74, s52
	v_lshlrev_b64 v[8:9], 2, v[0:1]
	v_readlane_b32 s8, v254, 48
	v_readlane_b32 s9, v254, 49
	s_addc_u32 s53, s75, s53
	v_readlane_b32 s5, v254, 45
	v_lshl_add_u64 v[2:3], s[8:9], 0, v[8:9]
	v_lshl_add_u64 v[8:9], s[52:53], 0, v[8:9]
	s_mov_b32 s53, -8
	v_readlane_b32 s6, v254, 46
	v_readlane_b32 s7, v254, 47
	v_readlane_b32 s10, v254, 50
	v_readlane_b32 s11, v254, 51
	v_readlane_b32 s12, v254, 52
	v_readlane_b32 s13, v254, 53
	v_readlane_b32 s14, v254, 54
	v_readlane_b32 s15, v254, 55
	v_readlane_b32 s16, v254, 56
	v_readlane_b32 s17, v254, 57
	v_readlane_b32 s18, v254, 58
	v_readlane_b32 s19, v254, 59
	v_lshl_add_u64 v[244:245], s[30:31], 0, v[8:9]
	v_add_co_u32_e32 v248, vcc, 0x2100000, v244
	v_lshl_add_u64 v[246:247], s[30:31], 0, v[6:7]
	s_nop 0
	v_addc_co_u32_e32 v249, vcc, 0, v245, vcc
	s_movk_i32 s4, 0x2000
	global_load_dword v219, v[244:245], off
	global_load_dword v220, v[248:249], off
	v_add_co_u32_e32 v248, vcc, s4, v246
	s_mov_b32 s54, 0x2102000
	s_nop 0
	v_addc_co_u32_e32 v249, vcc, 0, v247, vcc
	global_load_ushort v221, v[248:249], off
	v_add_co_u32_e32 v248, vcc, s4, v244
	s_nop 0
	s_nop 0
	v_addc_co_u32_e32 v249, vcc, 0, v245, vcc
	v_add_co_u32_e32 v250, vcc, s54, v244
	s_mov_b32 s54, 0x8000
	s_nop 0
	v_addc_co_u32_e32 v251, vcc, 0, v245, vcc
	v_add_co_u32_e32 v148, vcc, s54, v246
	s_mov_b32 s54, 0xe000
	s_nop 0
	v_addc_co_u32_e32 v149, vcc, 0, v247, vcc
	global_load_dword v222, v[248:249], off offset:-4096
	global_load_dword v223, v[250:251], off offset:-4096
	global_load_ushort v224, v[148:149], off
	global_load_dword v225, v[248:249], off
	global_load_dword v226, v[250:251], off
	v_add_co_u32_e32 v248, vcc, s54, v246
	s_mov_b32 s54, 0x2104000
	s_nop 0
	v_addc_co_u32_e32 v249, vcc, 0, v247, vcc
	global_load_ushort v227, v[248:249], off
	v_add_co_u32_e32 v248, vcc, s36, v244
	s_nop 1
	v_addc_co_u32_e32 v249, vcc, 0, v245, vcc
	v_add_co_u32_e32 v250, vcc, s54, v244
	s_mov_b32 s54, 0x14000
	s_nop 0
	v_addc_co_u32_e32 v251, vcc, 0, v245, vcc
	v_add_co_u32_e32 v148, vcc, s54, v246
	s_mov_b32 s54, 0x1a000
	s_nop 0
	v_addc_co_u32_e32 v149, vcc, 0, v247, vcc
	global_load_dword v228, v[248:249], off offset:-4096
	global_load_dword v229, v[250:251], off offset:-4096
	global_load_ushort v230, v[148:149], off
	global_load_dword v231, v[248:249], off
	s_nop 0
	global_load_dword v232, v[250:251], off
	v_add_co_u32_e32 v248, vcc, s54, v246
	s_mov_b32 s54, 0x2106000
	s_nop 0
	v_addc_co_u32_e32 v249, vcc, 0, v247, vcc
	global_load_ushort v233, v[248:249], off
	v_add_co_u32_e32 v248, vcc, s22, v244
	s_nop 1
	v_addc_co_u32_e32 v249, vcc, 0, v245, vcc
	v_add_co_u32_e32 v150, vcc, s54, v244
	s_mov_b32 s54, 0x26000
	s_nop 0
	v_addc_co_u32_e32 v151, vcc, 0, v245, vcc
	v_add_co_u32_e32 v152, vcc, s91, v246
	global_load_dword v234, v[248:249], off offset:-4096
	global_load_dword v235, v[150:151], off offset:-4096
	v_addc_co_u32_e32 v153, vcc, 0, v247, vcc
	global_load_ushort v236, v[152:153], off
	global_load_dword v237, v[248:249], off
	s_nop 0
	global_load_dword v238, v[150:151], off
	v_add_co_u32_e32 v150, vcc, s54, v246
	s_movk_i32 s54, 0x7000
	s_nop 0
	v_addc_co_u32_e32 v151, vcc, 0, v247, vcc
	global_load_ushort v239, v[150:151], off
	v_add_co_u32_e32 v150, vcc, s54, v244
	s_mov_b32 s54, 0x2107000
	s_nop 0
	v_addc_co_u32_e32 v151, vcc, 0, v245, vcc
	v_add_co_u32_e32 v244, vcc, s54, v244
	global_load_dword v240, v[150:151], off
	s_nop 0
	v_addc_co_u32_e32 v245, vcc, 0, v245, vcc
	global_load_dword v241, v[244:245], off
	v_add_co_u32_e32 v244, vcc, 0x2c000, v246
	s_nop 0
	s_nop 0
	v_addc_co_u32_e32 v245, vcc, 0, v247, vcc
	global_load_ushort v242, v[244:245], off
	s_mov_b64 s[54:55], 0x30000
	v_lshl_add_u64 v[6:7], v[6:7], 0, s[54:55]
	v_lshl_add_u64 v[8:9], v[8:9], 0, s[72:73]
	s_waitcnt vmcnt(0)
; DEVI float b2f(bfu b) { return __uint_as_float(((unsigned)b) << 16); }
; DEVI float geluf_(float x) { return 0.5f * x * (1.f + erff(x * 0.70710678118f)); }
; DEVI void apply_item(const Params& P, int l, int pass, int id, int tid) {
;     ...
;   for (int r0 = 0; r0 < 128; r0 += 8) {
;     float av[8], uv[8], gv[8];
; #pragma unroll
;     for (int i = 0; i < 8; ++i) {
;       long row = lt0 + r0 + i;
;       av[i] = AU0[row * 1024 + ch]; uv[i] = AU1[row * 1024 + ch];
;       gv[i] = b2f(Z[row * NCOL + 4 * 1024 + ch]);
;     }
; #pragma unroll
;     for (int i = 0; i < 8; ++i) {
;       int r = r0 + i;
;       if (t0.sample && (r & 31) == 0) hcur = P.in[4][(long)(l * 8 + t0.seq + (r >> 5)) * 1024 + ch];
;       hcur = av[i] * hcur + uv[i];
;       UB[(long)(lt0 + r) * 1024 + ch] = f2b(geluf_(gv[i]) * hcur);
.LBB0_650:
	v_mov_b32_e32 v10, v12
	v_mov_b32_e32 v11, v219
	v_mov_b32_e32 v29, v220
	v_mov_b32_e32 v34, v221
	v_mov_b32_e32 v31, v222
	v_mov_b32_e32 v27, v223
	v_mov_b32_e32 v33, v224
	v_mov_b32_e32 v28, v225
	v_mov_b32_e32 v23, v226
	v_mov_b32_e32 v32, v227
	v_mov_b32_e32 v25, v228
	v_mov_b32_e32 v19, v229
	v_mov_b32_e32 v30, v230
	v_mov_b32_e32 v21, v231
	v_mov_b32_e32 v17, v232
	v_mov_b32_e32 v26, v233
	v_mov_b32_e32 v18, v234
	v_mov_b32_e32 v15, v235
	v_mov_b32_e32 v24, v236
	v_mov_b32_e32 v16, v237
	v_mov_b32_e32 v13, v238
	v_mov_b32_e32 v22, v239
	v_mov_b32_e32 v14, v240
	v_mov_b32_e32 v20, v242
	v_mov_b32_e32 v12, v241
	s_add_i32 s52, s53, 8
	s_cmpk_gt_u32 s52, 0x77
	s_cbranch_scc1 .Lap_nopf
	v_lshl_add_u64 v[244:245], s[30:31], 0, v[8:9]
	v_add_co_u32_e32 v248, vcc, 0x2100000, v244
	v_lshl_add_u64 v[246:247], s[30:31], 0, v[6:7]
	s_nop 0
	v_addc_co_u32_e32 v249, vcc, 0, v245, vcc
	s_movk_i32 s4, 0x2000
	global_load_dword v219, v[244:245], off
	global_load_dword v220, v[248:249], off
	v_add_co_u32_e32 v248, vcc, s4, v246
	s_mov_b32 s54, 0x2102000
	s_nop 0
	v_addc_co_u32_e32 v249, vcc, 0, v247, vcc
	global_load_ushort v221, v[248:249], off
	v_add_co_u32_e32 v248, vcc, s4, v244
	s_nop 0
	s_nop 0
	v_addc_co_u32_e32 v249, vcc, 0, v245, vcc
	v_add_co_u32_e32 v250, vcc, s54, v244
	s_mov_b32 s54, 0x8000
	s_nop 0
	v_addc_co_u32_e32 v251, vcc, 0, v245, vcc
	v_add_co_u32_e32 v148, vcc, s54, v246
	s_mov_b32 s54, 0xe000
	s_nop 0
	v_addc_co_u32_e32 v149, vcc, 0, v247, vcc
	global_load_dword v222, v[248:249], off offset:-4096
	global_load_dword v223, v[250:251], off offset:-4096
	global_load_ushort v224, v[148:149], off
	global_load_dword v225, v[248:249], off
	global_load_dword v226, v[250:251], off
	v_add_co_u32_e32 v248, vcc, s54, v246
	s_mov_b32 s54, 0x2104000
	s_nop 0
	v_addc_co_u32_e32 v249, vcc, 0, v247, vcc
	global_load_ushort v227, v[248:249], off
	v_add_co_u32_e32 v248, vcc, s36, v244
	s_nop 1
	v_addc_co_u32_e32 v249, vcc, 0, v245, vcc
	v_add_co_u32_e32 v250, vcc, s54, v244
	s_mov_b32 s54, 0x14000
	s_nop 0
	v_addc_co_u32_e32 v251, vcc, 0, v245, vcc
	v_add_co_u32_e32 v148, vcc, s54, v246
	s_mov_b32 s54, 0x1a000
	s_nop 0
	v_addc_co_u32_e32 v149, vcc, 0, v247, vcc
	global_load_dword v228, v[248:249], off offset:-4096
	global_load_dword v229, v[250:251], off offset:-4096
	global_load_ushort v230, v[148:149], off
	global_load_dword v231, v[248:249], off
	s_nop 0
	global_load_dword v232, v[250:251], off
	v_add_co_u32_e32 v248, vcc, s54, v246
	s_mov_b32 s54, 0x2106000
	s_nop 0
	v_addc_co_u32_e32 v249, vcc, 0, v247, vcc
	global_load_ushort v233, v[248:249], off
	v_add_co_u32_e32 v248, vcc, s22, v244
	s_nop 1
	v_addc_co_u32_e32 v249, vcc, 0, v245, vcc
	v_add_co_u32_e32 v150, vcc, s54, v244
	s_mov_b32 s54, 0x26000
	s_nop 0
	v_addc_co_u32_e32 v151, vcc, 0, v245, vcc
	v_add_co_u32_e32 v152, vcc, s91, v246
	global_load_dword v234, v[248:249], off offset:-4096
	global_load_dword v235, v[150:151], off offset:-4096
	v_addc_co_u32_e32 v153, vcc, 0, v247, vcc
	global_load_ushort v236, v[152:153], off
	global_load_dword v237, v[248:249], off
	s_nop 0
	global_load_dword v238, v[150:151], off
	v_add_co_u32_e32 v150, vcc, s54, v246
	s_movk_i32 s54, 0x7000
	s_nop 0
	v_addc_co_u32_e32 v151, vcc, 0, v247, vcc
	global_load_ushort v239, v[150:151], off
	v_add_co_u32_e32 v150, vcc, s54, v244
	s_mov_b32 s54, 0x2107000
	s_nop 0
	v_addc_co_u32_e32 v151, vcc, 0, v245, vcc
	v_add_co_u32_e32 v244, vcc, s54, v244
	global_load_dword v240, v[150:151], off
	s_nop 0
	v_addc_co_u32_e32 v245, vcc, 0, v245, vcc
	global_load_dword v241, v[244:245], off
	v_add_co_u32_e32 v244, vcc, 0x2c000, v246
	s_nop 0
	s_nop 0
	v_addc_co_u32_e32 v245, vcc, 0, v247, vcc
	global_load_ushort v242, v[244:245], off
	s_mov_b64 s[54:55], 0x30000
	v_lshl_add_u64 v[6:7], v[6:7], 0, s[54:55]
	v_lshl_add_u64 v[8:9], v[8:9], 0, s[72:73]
.Lap_nopf:
	s_lshr_b32 s54, s52, 5
	s_add_i32 s54, s51, s54
	s_ashr_i32 s55, s54, 31
	s_lshl_b64 s[74:75], s[54:55], 12
	s_and_b32 s54, s52, 24
	s_cmp_eq_u32 s54, 0
	s_cselect_b64 s[54:55], -1, 0
	s_xor_b64 s[56:57], s[26:27], -1
	s_and_b64 s[54:55], s[56:57], s[54:55]
	s_and_b64 vcc, exec, s[54:55]
	s_cbranch_vccz .LBB0_652
	v_lshl_add_u64 v[36:37], v[2:3], 0, s[74:75]
	global_load_dword v10, v[36:37], off
	s_waitcnt vmcnt(0)
.LBB0_652:
	v_lshlrev_b32_e32 v34, 16, v34
	v_mul_f32_e32 v35, 0x3f3504f3, v34
	v_cmp_nlt_f32_e64 s[54:55], |v35|, 1.0
	s_and_saveexec_b64 s[56:57], s[54:55]
	s_xor_b64 s[76:77], exec, s[56:57]
	s_cbranch_execz .LBB0_654
	v_fma_f32 v36, |v35|, s70, v188
	v_fma_f32 v36, |v35|, v36, s71
	v_fma_f32 v36, |v35|, v36, s3
	v_fma_f32 v36, |v35|, v36, s96
	v_fma_f32 v36, |v35|, v36, s97
	v_fma_f32 v36, |v35|, v36, s87
	v_fma_f32 v36, |v35|, v36, |v35|
	v_mul_f32_e32 v37, 0xbfb8aa3b, v36
	v_fma_f32 v38, v36, s94, -v37
	v_rndne_f32_e32 v39, v37
	v_fmac_f32_e32 v38, 0xb2a5705f, v36
	v_sub_f32_e32 v37, v37, v39
	v_add_f32_e32 v37, v37, v38
	v_cvt_i32_f32_e32 v38, v39
	v_exp_f32_e32 v37, v37
	v_cmp_nlt_f32_e32 vcc, s95, v36
	v_ldexp_f32 v37, v37, v38
	s_nop 0
	v_cndmask_b32_e32 v37, 0, v37, vcc
	v_cmp_ngt_f32_e32 vcc, s68, v36
	s_nop 1
	v_cndmask_b32_e32 v36, v189, v37, vcc
	v_sub_f32_e32 v36, 1.0, v36
.LBB0_654:
	s_andn2_saveexec_b64 s[76:77], s[76:77]
	v_mul_f32_e32 v36, v35, v35
	v_fmamk_f32 v37, v36, 0xba1345e1, v99
	v_fmaak_f32 v37, v36, v37, 0xbcdac9b8
	v_fmaak_f32 v37, v36, v37, 0x3de703be
	v_fmaak_f32 v37, v36, v37, 0xbec09330
	v_fmaak_f32 v36, v36, v37, 0x3e0375d0
	v_fma_f32 v36, |v35|, v36, |v35|
	s_or_b64 exec, exec, s[76:77]
	v_fmac_f32_e32 v29, v11, v10
	v_bfi_b32 v11, s35, v36, v35
	v_mul_f32_e32 v10, 0.5, v34
	v_add_f32_e32 v11, 1.0, v11
	v_mul_f32_e32 v10, v10, v11
	v_mul_f32_e32 v10, v29, v10
	v_bfe_u32 v11, v10, 16, 1
	v_lshlrev_b32_e32 v33, 16, v33
	v_add3_u32 v34, v10, v11, s39
	v_lshl_add_u64 v[10:11], s[30:31], 0, v[4:5]
	global_store_short_d16_hi v[10:11], v34, off
	v_mul_f32_e32 v34, 0x3f3504f3, v33
	v_cmp_nlt_f32_e64 s[54:55], |v34|, 1.0
	s_and_saveexec_b64 s[56:57], s[54:55]
	s_xor_b64 s[76:77], exec, s[56:57]
	s_cbranch_execz .LBB0_658
	v_fma_f32 v35, |v34|, s70, v188
	v_fma_f32 v35, |v34|, v35, s71
	v_fma_f32 v35, |v34|, v35, s3
	v_fma_f32 v35, |v34|, v35, s96
	v_fma_f32 v35, |v34|, v35, s97
	v_fma_f32 v35, |v34|, v35, s87
	v_fma_f32 v35, |v34|, v35, |v34|
	v_mul_f32_e32 v36, 0xbfb8aa3b, v35
	v_fma_f32 v37, v35, s94, -v36
	v_rndne_f32_e32 v38, v36
	v_fmac_f32_e32 v37, 0xb2a5705f, v35
	v_sub_f32_e32 v36, v36, v38
	v_add_f32_e32 v36, v36, v37
	v_cvt_i32_f32_e32 v37, v38
	v_exp_f32_e32 v36, v36
	v_cmp_nlt_f32_e32 vcc, s95, v35
	v_ldexp_f32 v36, v36, v37
	s_nop 0
	v_cndmask_b32_e32 v36, 0, v36, vcc
	v_cmp_ngt_f32_e32 vcc, s68, v35
	s_nop 1
	v_cndmask_b32_e32 v35, v189, v36, vcc
	v_sub_f32_e32 v35, 1.0, v35

; DEVI float b2f(bfu b) { return __uint_as_float(((unsigned)b) << 16); }
; DEVI float geluf_(float x) { return 0.5f * x * (1.f + erff(x * 0.70710678118f)); }
; DEVI void apply_item(const Params& P, int l, int pass, int id, int tid) {
;     ...
;   for (int r0 = 0; r0 < 128; r0 += 8) {
;     float av[8], uv[8], gv[8];
; #pragma unroll
;     for (int i = 0; i < 8; ++i) {
;       long row = lt0 + r0 + i;
;       av[i] = AU0[row * 1024 + ch]; uv[i] = AU1[row * 1024 + ch];
;       gv[i] = b2f(Z[row * NCOL + 4 * 1024 + ch]);
;     }
; #pragma unroll
;     for (int i = 0; i < 8; ++i) {
;       int r = r0 + i;
;       if (t0.sample && (r & 31) == 0) hcur = P.in[4][(long)(l * 8 + t0.seq + (r >> 5)) * 1024 + ch];
;       hcur = av[i] * hcur + uv[i];
;       UB[(long)(lt0 + r) * 1024 + ch] = f2b(geluf_(gv[i]) * hcur);
.LBB0_686:
	s_mov_b64 s[54:55], 0x4000
	v_lshl_add_u64 v[4:5], v[4:5], 0, s[54:55]
	s_cmpk_gt_u32 s52, 0x77
	s_cbranch_scc1 .LBB0_688
	s_mov_b32 s53, s52
	s_waitcnt vmcnt(8)
	s_branch .LBB0_650
